# code placement: 4 bytes of padding after the first-item loader (all later code shifted by 4)
# baseline (speedup 1.0000x reference)
.Lrl0_now12:
	s_mov_b64 exec, s[28:29]
	s_nop 0
.LBB0_63:
	s_or_b64 exec, exec, s[20:21]
	s_and_saveexec_b64 s[0:1], s[8:9]
	s_cbranch_execz .LBB0_65
	v_lshl_add_u64 v[2:3], v[82:83], 0, v[166:167]
	v_lshlrev_b64 v[2:3], 6, v[2:3]
	v_lshl_add_u64 v[2:3], s[68:69], 0, v[2:3]
	v_lshlrev_b32_e32 v0, 2, v7
	v_lshl_add_u64 v[2:3], v[2:3], 0, v[0:1]
	global_load_dword v4, v[2:3], off
	global_load_dword v5, v0, s[12:13]
	s_nop 0
	global_load_dword v0, v0, s[10:11]
	s_nop 0
	global_load_dword v2, v[2:3], off offset:32
	s_mov_b32 s18, 0x800000
	v_mov_b32_e32 v3, v222
	v_mov_b32_e32 v6, v222
	v_lshl_add_u32 v3, v3, 2, -4
	v_mov_b32_e32 v7, v222
	v_lshl_add_u32 v6, v6, 2, -8
	v_mov_b32_e32 v8, v222
	v_mov_b32_e32 v9, v222
	v_mov_b32_e32 v10, v222
	s_waitcnt vmcnt(0) lgkmcnt(0)
	v_add_f32_e32 v4, v4, v5
	v_mul_f32_e32 v5, 0x3fb8aa3b, v4
	v_exp_f32_e32 v5, v5
	v_mul_f32_e32 v0, 0x3fb8aa3b, v0
	v_exp_f32_e32 v0, v0
	v_mul_f32_e32 v2, 0xbfb8aa3b, v2
	v_add_f32_e32 v5, 1.0, v5
	v_cmp_gt_f32_e32 vcc, s18, v5
	s_mov_b32 s18, 0x3f317217
	v_exp_f32_e32 v2, v2
	v_cndmask_b32_e64 v11, 0, 32, vcc
	v_ldexp_f32 v5, v5, v11
	v_log_f32_e32 v5, v5
	v_mov_b32_e32 v11, 0x41b17218
	v_cndmask_b32_e32 v11, 0, v11, vcc
	v_add_f32_e32 v2, 1.0, v2
	v_mul_f32_e32 v12, 0x3f317217, v5
	v_fma_f32 v12, v5, s18, -v12
	v_fmac_f32_e32 v12, 0x3377d1cf, v5
	s_mov_b32 s18, 0x7f800000
	v_fmac_f32_e32 v12, 0x3f317217, v5
	v_cmp_lt_f32_e64 vcc, |v5|, s18
	s_mov_b32 s18, 0x41a00000
	s_nop 0
	v_cndmask_b32_e32 v5, v5, v12, vcc
	v_sub_f32_e32 v5, v5, v11
	v_cmp_lt_f32_e32 vcc, s18, v4
	s_nop 1
	v_cndmask_b32_e32 v4, v5, v4, vcc
	v_mul_f32_e64 v5, v4, -v0
	ds_bpermute_b32 v3, v3, v5
	s_waitcnt lgkmcnt(0)
	v_fma_f32 v0, v4, -v0, v3
	v_cndmask_b32_e64 v0, v0, v5, s[42:43]
	ds_bpermute_b32 v3, v6, v0
	v_lshl_add_u32 v4, v7, 2, -16
	v_not_b32_e32 v5, 31
	v_lshl_add_u32 v5, v8, 2, v5
	v_lshl_add_u32 v6, v10, 2, v225
	s_waitcnt lgkmcnt(0)
	v_add_f32_e32 v3, v0, v3
	v_cndmask_b32_e64 v0, v3, v0, s[44:45]
	ds_bpermute_b32 v3, v4, v0
	v_lshl_add_u32 v4, v9, 2, v224
	s_waitcnt lgkmcnt(0)
	v_add_f32_e32 v3, v0, v3
	v_cndmask_b32_e64 v0, v3, v0, s[46:47]
	ds_bpermute_b32 v3, v5, v0
	v_div_scale_f32 v5, s[18:19], v2, v2, 1.0
	v_rcp_f32_e32 v7, v5
	s_waitcnt lgkmcnt(0)
	v_add_f32_e32 v3, v0, v3
	v_cndmask_b32_e64 v0, v3, v0, s[48:49]
	ds_bpermute_b32 v3, v4, v0
	v_fma_f32 v8, -v5, v7, 1.0
	v_div_scale_f32 v4, vcc, 1.0, v2, 1.0
	v_fmac_f32_e32 v7, v8, v7
	s_waitcnt lgkmcnt(0)
	v_add_f32_e32 v3, v0, v3
	v_cndmask_b32_e64 v0, v3, v0, s[50:51]
	ds_bpermute_b32 v3, v6, v0
	v_mul_f32_e32 v6, v4, v7
	v_fma_f32 v8, -v5, v6, v4
	v_fmac_f32_e32 v6, v8, v7
	v_fma_f32 v4, -v5, v6, v4
	s_waitcnt lgkmcnt(0)
	v_add_f32_e32 v3, v0, v3
	v_cndmask_b32_e64 v0, v3, v0, s[52:53]
	v_div_fmas_f32 v3, v4, v7, v6
	v_mul_f32_e32 v4, 0x3fb8aa3b, v0
	v_exp_f32_e32 v4, v4
	v_div_fixup_f32 v2, v3, v2, 1.0
	ds_write_b32 v114, v2
	ds_write2st64_b32 v41, v0, v2 offset1:2
	v_mul_f32_e32 v0, v2, v4
	ds_write_b32 v41, v0 offset:768
